# sel-branch att_step2 path: drop accumulator phi copies
# speedup vs baseline: 1.0132x; 1.0132x over previous
.Lsel_loop_nocopy:
	s_cmp_lt_u32 s9, s17
	s_cselect_b64 s[24:25], -1, 0
	s_cmp_ge_u32 s9, s17
	s_cbranch_scc1 .LBB0_1321

.LBB0_1333:
	s_andn2_b64 vcc, exec, s[24:25]
	s_cbranch_vccz .Lsel_fast_store
	s_branch .Lsel_fast_tail

.Lsel_fast_tail:
	s_add_i32 s22, s22, 2
	s_add_i32 s9, s9, 1
	s_cmp_eq_u32 s31, s22
	v_add_u32_e32 v246, 0x80, v246
	s_waitcnt lgkmcnt(0)
	s_barrier
	s_cbranch_scc1 .Lsel_fast_exit
	v_mov_b32_e32 v2, v252
	s_branch .Lsel_loop_nocopy
.Lsel_fast_exit:
	s_nop 7
	v_mov_b64_e32 v[80:81], v[48:49]
	v_mov_b64_e32 v[64:65], v[32:33]
	v_mov_b32_e32 v250, v243
	v_mov_b64_e32 v[78:79], v[46:47]
	v_mov_b64_e32 v[76:77], v[44:45]
	v_mov_b64_e32 v[74:75], v[42:43]
	v_mov_b64_e32 v[72:73], v[40:41]
	v_mov_b64_e32 v[70:71], v[38:39]
	v_mov_b64_e32 v[68:69], v[36:37]
	v_mov_b64_e32 v[66:67], v[34:35]
	v_mov_b64_e32 v[62:63], v[30:31]
	v_mov_b64_e32 v[60:61], v[28:29]
	v_mov_b64_e32 v[58:59], v[26:27]
	v_mov_b64_e32 v[56:57], v[24:25]
	v_mov_b64_e32 v[54:55], v[22:23]
	v_mov_b64_e32 v[52:53], v[20:21]
	v_mov_b64_e32 v[50:51], v[18:19]
	s_branch .Lsel_exit

.Lsel_exit:
	v_mov_b32_e32 v2, v252
	s_nop 1
	v_permlane32_swap_b32_e32 v252, v2
	v_mov_b32_e32 v5, v0
	v_add_f32_e32 v4, v252, v2
	v_mov_b32_e32 v2, 0
	v_readfirstlane_b32 s0, v5
	v_cmp_lt_f32_e32 vcc, 0, v4
	s_and_saveexec_b64 s[2:3], vcc
	v_readlane_b32 s48, v255, 60
	v_readlane_b32 s49, v255, 61
	v_readlane_b32 s23, v255, 41
	s_cbranch_execz .LBB0_1363
	s_add_i32 s1, s12, s21
	s_ashr_i32 s0, s0, 3
	v_lshrrev_b32_e32 v2, 2, v5
	s_and_b32 s0, s0, -8
	v_and_or_b32 v2, v2, 7, s1
	v_add_u32_e32 v2, s0, v2
	v_mov_b64_e32 v[6:7], s[48:49]
	s_movk_i32 s0, 0xc0
	v_mad_i64_i32 v[6:7], s[0:1], v2, s0, v[6:7]
	v_and_or_b32 v2, v5, 3, s23
	v_mul_u32_u24_e32 v2, 3, v2
	v_lshlrev_b32_e32 v2, 2, v2
	v_lshl_add_u64 v[6:7], v[6:7], 0, v[2:3]
	global_load_dword v2, v[6:7], off offset:4
	s_waitcnt vmcnt(0)
	v_div_scale_f32 v5, s[0:1], v4, v4, v2
	v_rcp_f32_e32 v6, v5
	v_div_scale_f32 v7, vcc, v2, v4, v2
	v_fma_f32 v8, -v5, v6, 1.0
	v_fmac_f32_e32 v6, v8, v6
	v_mul_f32_e32 v8, v7, v6
	v_fma_f32 v9, -v5, v8, v7
	v_fmac_f32_e32 v8, v9, v6
	v_fma_f32 v5, -v5, v8, v7
	v_div_fmas_f32 v5, v5, v6, v8
	v_div_fixup_f32 v2, v5, v4, v2
